# v55: v53 + waiting workgroups issue their L1 acquire (buffer_inv sc1) at arrival, in front of the first poll, so it overlaps the wait
# speedup vs baseline: 1.0062x; 1.0062x over previous
.LBB0_237:
	s_or_b64 exec, exec, s[4:5]
	v_cvt_f32_u32_e32 v4, v2
	s_waitcnt vmcnt(0)
	v_readfirstlane_b32 s4, v3
	v_sub_u32_e32 v3, 0, v2
	v_rcp_iflag_f32_e32 v4, v4
	v_add_u32_e32 v5, s4, v1
	v_mul_f32_e32 v4, 0x4f7ffffe, v4
	v_cvt_u32_f32_e32 v4, v4
	v_mul_lo_u32 v1, v3, v4
	v_mul_hi_u32 v1, v4, v1
	v_add_u32_e32 v1, v4, v1
	v_mul_hi_u32 v1, v5, v1
	v_mul_lo_u32 v3, v1, v2
	v_sub_u32_e32 v3, v5, v3
	v_add_u32_e32 v4, 1, v1
	v_cmp_ge_u32_e32 vcc, v3, v2
	s_nop 1
	v_cndmask_b32_e32 v1, v1, v4, vcc
	v_sub_u32_e32 v4, v3, v2
	v_cndmask_b32_e32 v3, v3, v4, vcc
	v_add_u32_e32 v4, 1, v1
	v_cmp_ge_u32_e32 vcc, v3, v2
	v_add_u32_e32 v3, 1, v5
	s_nop 0
	v_cndmask_b32_e32 v1, v1, v4, vcc
	v_mul_lo_u32 v4, v2, v1
	v_add_u32_e32 v2, v4, v2
	v_cmp_ne_u32_e32 vcc, v3, v2
	s_and_saveexec_b64 s[4:5], vcc
	s_xor_b64 s[4:5], exec, s[4:5]
	s_cbranch_execz .LBB0_251
	v_readlane_b32 s6, v254, 33
	v_readlane_b32 s7, v254, 34
	s_waitcnt lgkmcnt(0)
	s_nop 3
	buffer_inv sc1
	global_load_dword v0, v201, s[6:7] sc1
	s_waitcnt vmcnt(0)
	v_cmp_eq_u32_e32 vcc, v0, v1
	s_and_saveexec_b64 s[6:7], vcc
	s_cbranch_execz .LBB0_250
	s_mov_b32 s14, 1
	s_mov_b64 s[34:35], 0
	s_branch .LBB0_241

.LBB0_250:
	s_or_b64 exec, exec, s[6:7]
	s_waitcnt vmcnt(0)
	s_waitcnt vmcnt(0)

.LBB0_485:
	s_or_b64 exec, exec, s[4:5]
	v_cvt_f32_u32_e32 v4, v2
	s_waitcnt vmcnt(0)
	v_readfirstlane_b32 s4, v3
	v_sub_u32_e32 v3, 0, v2
	v_rcp_iflag_f32_e32 v4, v4
	v_add_u32_e32 v5, s4, v1
	v_mul_f32_e32 v4, 0x4f7ffffe, v4
	v_cvt_u32_f32_e32 v4, v4
	v_mul_lo_u32 v1, v3, v4
	v_mul_hi_u32 v1, v4, v1
	v_add_u32_e32 v1, v4, v1
	v_mul_hi_u32 v1, v5, v1
	v_mul_lo_u32 v3, v1, v2
	v_sub_u32_e32 v3, v5, v3
	v_add_u32_e32 v4, 1, v1
	v_cmp_ge_u32_e32 vcc, v3, v2
	s_nop 1
	v_cndmask_b32_e32 v1, v1, v4, vcc
	v_sub_u32_e32 v4, v3, v2
	v_cndmask_b32_e32 v3, v3, v4, vcc
	v_add_u32_e32 v4, 1, v1
	v_cmp_ge_u32_e32 vcc, v3, v2
	v_add_u32_e32 v3, 1, v5
	s_nop 0
	v_cndmask_b32_e32 v1, v1, v4, vcc
	v_mul_lo_u32 v4, v2, v1
	v_add_u32_e32 v2, v4, v2
	v_cmp_ne_u32_e32 vcc, v3, v2
	s_and_saveexec_b64 s[4:5], vcc
	s_xor_b64 s[4:5], exec, s[4:5]
	s_cbranch_execz .LBB0_499
	v_readlane_b32 s6, v254, 33
	v_readlane_b32 s7, v254, 34
	s_waitcnt lgkmcnt(0)
	s_nop 3
	buffer_inv sc1
	global_load_dword v0, v201, s[6:7] sc1
	s_waitcnt vmcnt(0)
	v_cmp_eq_u32_e32 vcc, v0, v1
	s_and_saveexec_b64 s[6:7], vcc
	s_cbranch_execz .LBB0_498
	s_mov_b32 s16, 1
	s_mov_b64 s[34:35], 0
	s_branch .LBB0_489
